# mixers queue: mLSTM items claim their next queue index in their last chunk (same lane-50/51 mechanism the attention items use), removing the exposed atomic round trip between items
# speedup vs baseline: 1.0017x; 1.0017x over previous
.LBB0_662:
	s_or_b64 exec, exec, s[90:91]
	s_branch .Lml_pf_skip0
.Lml_claim0:
	v_readfirstlane_b32 s98, v163
	s_cmp_lg_u32 s98, 0
	s_cbranch_scc1 .Lml_pf_skip0
	v_readlane_b32 s98, v254, 40
	v_readlane_b32 s99, v254, 41
	s_mov_b32 exec_lo, 0
	s_mov_b32 exec_hi, 0x40000
	s_nop 4
	global_atomic_add v255, v1, v171, s[98:99] offset:256 sc0
	s_mov_b64 exec, -1
	s_mov_b32 s98, 1
	v_writelane_b32 v255, s98, 51
